# EL phase: the eight loop-invariant mix coefficients read once before the loop instead of one dword at a time with vmcnt(0) per element
# speedup vs baseline: 1.0099x; 1.0018x over previous
; #define KAS __attribute__((address_space(4)))
; __device__ __forceinline__ void unpack8(const u32x4 w, float (&f)[8]) { f[0] = bflo(w.x); f[1] = bfhi(w.x); f[2] = bflo(w.y); f[3] = bfhi(w.y); f[4] = bflo(w.z); f[5] = bfhi(w.z); f[6] = bflo(w.w); f[7] = bfhi(w.w); }
; __device__ __forceinline__ void el_phase(const KAS Args& a, int i, const int tid_, const int bid, const int nblk) {
;     const bf16_t* Z = (const bf16_t*)(a.ws + WS_HZ); bf16_t* LA = (bf16_t*)((unsigned char*)a.out + OUT_LA);
;     const float* mu = a.mu + i * 1792 + 1536;
;     const int gt = bid * 512 + tid_, NGT = nblk * 512;
;     for (int ib = gt; ib < M * 32; ib += 4 * NGT) { u32x4 rc[4], rp[4];
; #pragma unroll
;         for (int k = 0; k < 4; ++k) { const int idx = ib + k * NGT; const int ii = idx < M * 32 ? idx : ib; const int m = ii >> 5, c0 = (ii & 31) * 8, t = m & (T - 1);
;             rc[k] = *(const u32x4*)(Z + (size_t)m * ZC + 1536 + c0); rp[k] = (t > 0) ? *(const u32x4*)(Z + (size_t)(m - 1) * ZC + 1536 + c0) : (u32x4){0u, 0u, 0u, 0u}; }
; #pragma unroll
;         for (int k = 0; k < 4; ++k) { const int idx = ib + k * NGT; if (idx >= M * 32) break; const int m = idx >> 5, c0 = (idx & 31) * 8;
;             float zc[8], zp[8], o[8]; unpack8(rc[k], zc); unpack8(rp[k], zp);
; #pragma unroll
;             for (int e = 0; e < 8; ++e) { const float z = zc[e] + (zp[e] - zc[e]) * mu[c0 + e];
.LBB0_196:
	s_andn2_b64 vcc, exec, s[2:3]
	s_cbranch_vccnz .LBB0_496
	v_readlane_b32 s2, v255, 21
	s_cmp_lt_i32 s2, 4
	s_cbranch_scc1 .LBB0_201
	s_cmp_lt_i32 s2, 5
	s_mov_b64 s[2:3], -1
	s_mov_b32 s27, 0x200000
	s_mov_b32 s28, 0x1fffff
	s_cbranch_scc0 .LBB0_344
	s_waitcnt vmcnt(8)
	v_lshl_add_u32 v5, s91, 9, v186
	v_cmp_gt_i32_e32 vcc, s27, v5
	s_and_saveexec_b64 s[14:15], vcc
	s_cbranch_execz .LBB0_343
	s_load_dwordx2 s[2:3], s[84:85], 0x118
	s_load_dwordx2 s[6:7], s[84:85], 0x60
	s_mul_i32 s92, s83, 0x700
	v_lshlrev_b32_e32 v0, 3, v186
	v_lshl_add_u32 v38, s91, 12, v0
	s_waitcnt lgkmcnt(0)
	s_add_u32 s16, s2, 0x8000000
	s_addc_u32 s17, s3, 0
	s_lshl_b64 s[2:3], s[92:93], 2
	s_add_u32 s2, s6, s2
	s_addc_u32 s3, s7, s3
	s_add_u32 s18, s2, 0x1800
	s_addc_u32 s19, s3, 0
	s_lshl_b32 s24, s90, 9
	s_lshl_b32 s25, s90, 10
	s_lshl_b32 s26, s90, 14
	s_mov_b64 s[20:21], 0
	v_and_b32_e32 v78, 0xf8, v38
	v_lshlrev_b32_e32 v78, 2, v78
	global_load_dwordx4 v[46:49], v78, s[18:19]
	global_load_dwordx4 v[50:53], v78, s[18:19] offset:16
	s_waitcnt vmcnt(0)
	s_branch .LBB0_204

; __device__ __forceinline__ void el_phase(const KAS Args& a, int i, const int tid_, const int bid, const int nblk) {
;     ...
;     for (int ib = gt; ib < M * 32; ib += 4 * NGT) { u32x4 rc[4], rp[4];
; #pragma unroll
;         for (int k = 0; k < 4; ++k) { const int idx = ib + k * NGT; const int ii = idx < M * 32 ? idx : ib; const int m = ii >> 5, c0 = (ii & 31) * 8, t = m & (T - 1);
;             rc[k] = *(const u32x4*)(Z + (size_t)m * ZC + 1536 + c0); rp[k] = (t > 0) ? *(const u32x4*)(Z + (size_t)(m - 1) * ZC + 1536 + c0) : (u32x4){0u, 0u, 0u, 0u}; }
.LBB0_204:
	v_ashrrev_i32_e32 v36, 5, v5
	v_and_b32_e32 v42, 0xf8, v38
	v_mov_b64_e32 v[0:1], s[80:81]
	v_mad_i64_i32 v[0:1], s[2:3], v36, s33, v[0:1]
	v_lshlrev_b32_e32 v2, 1, v42
	v_lshl_add_u64 v[0:1], v[0:1], 0, v[2:3]
	global_load_dwordx4 v[28:31], v[0:1], off offset:3072
	v_and_b32_e32 v0, 0x1ffe0, v5
	v_ashrrev_i32_e32 v37, 31, v36
	v_mov_b32_e32 v20, 0
	v_cmp_ne_u32_e32 vcc, 0, v0
	v_mov_b32_e32 v32, 0
	v_mov_b32_e32 v33, 0
	v_mov_b32_e32 v34, 0
	v_mov_b32_e32 v35, 0
	s_and_saveexec_b64 s[2:3], vcc
	s_cbranch_execz .LBB0_206
	v_add_u32_e32 v4, -1, v36
	v_mov_b64_e32 v[0:1], s[80:81]
	v_mad_i64_i32 v[0:1], s[6:7], v4, s33, v[0:1]
	v_lshl_add_u64 v[0:1], v[0:1], 0, v[2:3]
	global_load_dwordx4 v[32:35], v[0:1], off offset:3072

; __device__ __forceinline__ float fast_sigmoid(float x) { return __builtin_amdgcn_rcpf(1.0f + __builtin_amdgcn_exp2f(-1.4426950408889634f * x)); }
; __device__ __forceinline__ void el_phase(const KAS Args& a, int i, const int tid_, const int bid, const int nblk) {
;     ...
;             for (int e = 0; e < 8; ++e) { const float z = zc[e] + (zp[e] - zc[e]) * mu[c0 + e];
;                 o[e] = (c0 < 64) ? (2.0f * fast_sigmoid(2.0f * z) - 1.0f) : (c0 < 128 ? z : fast_sigmoid(z)); }
.LBB0_212:
	s_or_b64 exec, exec, s[2:3]
	s_waitcnt vmcnt(0)
	v_lshlrev_b32_e32 v1, 16, v28
	v_lshlrev_b32_e32 v0, 16, v32
	s_movk_i32 s2, 0x80
	v_sub_f32_e32 v43, v0, v1
	v_lshlrev_b32_e32 v0, 2, v42
	v_cmp_lt_u32_e64 s[6:7], 63, v42
	v_cmp_gt_u32_e32 vcc, s2, v42
	v_mov_b32_e32 v42, v46
	v_fmac_f32_e32 v1, v43, v42
	s_and_saveexec_b64 s[2:3], s[6:7]
	s_xor_b64 s[2:3], exec, s[2:3]
	s_cbranch_execz .LBB0_214
	v_mul_f32_e32 v42, 0xbfb8aa3b, v1
	v_exp_f32_e32 v42, v42
	s_nop 0
	v_add_f32_e32 v42, 1.0, v42
	v_rcp_f32_e32 v42, v42
	s_nop 0
	v_cndmask_b32_e32 v42, v42, v1, vcc

; __device__ __forceinline__ float fast_sigmoid(float x) { return __builtin_amdgcn_rcpf(1.0f + __builtin_amdgcn_exp2f(-1.4426950408889634f * x)); }
; __device__ __forceinline__ void el_phase(const KAS Args& a, int i, const int tid_, const int bid, const int nblk) {
;     ...
;             for (int e = 0; e < 8; ++e) { const float z = zc[e] + (zp[e] - zc[e]) * mu[c0 + e];
;                 o[e] = (c0 < 64) ? (2.0f * fast_sigmoid(2.0f * z) - 1.0f) : (c0 < 128 ? z : fast_sigmoid(z)); }
.LBB0_216:
	s_or_b64 exec, exec, s[2:3]
	v_mov_b32_e32 v1, v3
	v_lshl_add_u64 v[0:1], s[18:19], 0, v[0:1]
	v_mov_b32_e32 v43, v47
	v_and_b32_e32 v28, 0xffff0000, v28
	v_and_b32_e32 v32, 0xffff0000, v32
	v_sub_f32_e32 v32, v32, v28
	v_fmac_f32_e32 v28, v32, v43
	s_and_saveexec_b64 s[2:3], s[6:7]
	s_xor_b64 s[2:3], exec, s[2:3]
	s_cbranch_execz .LBB0_218
	v_mul_f32_e32 v32, 0xbfb8aa3b, v28
	v_exp_f32_e32 v32, v32
	s_nop 0
	v_add_f32_e32 v32, 1.0, v32
	v_rcp_f32_e32 v32, v32
	s_nop 0
	v_cndmask_b32_e32 v32, v32, v28, vcc

; __device__ __forceinline__ float fast_sigmoid(float x) { return __builtin_amdgcn_rcpf(1.0f + __builtin_amdgcn_exp2f(-1.4426950408889634f * x)); }
; __device__ __forceinline__ void el_phase(const KAS Args& a, int i, const int tid_, const int bid, const int nblk) {
;     ...
;             for (int e = 0; e < 8; ++e) { const float z = zc[e] + (zp[e] - zc[e]) * mu[c0 + e];
;                 o[e] = (c0 < 64) ? (2.0f * fast_sigmoid(2.0f * z) - 1.0f) : (c0 < 128 ? z : fast_sigmoid(z)); }
.LBB0_220:
	s_or_b64 exec, exec, s[2:3]
	v_mov_b32_e32 v44, v48
	v_lshlrev_b32_e32 v28, 16, v29
	v_lshlrev_b32_e32 v43, 16, v33
	v_sub_f32_e32 v43, v43, v28
	v_fmac_f32_e32 v28, v43, v44
	s_and_saveexec_b64 s[2:3], s[6:7]
	s_xor_b64 s[2:3], exec, s[2:3]
	s_cbranch_execz .LBB0_222
	v_mul_f32_e32 v43, 0xbfb8aa3b, v28
	v_exp_f32_e32 v43, v43
	s_nop 0
	v_add_f32_e32 v43, 1.0, v43
	v_rcp_f32_e32 v43, v43
	s_nop 0
	v_cndmask_b32_e32 v43, v43, v28, vcc

; __device__ __forceinline__ float fast_sigmoid(float x) { return __builtin_amdgcn_rcpf(1.0f + __builtin_amdgcn_exp2f(-1.4426950408889634f * x)); }
; __device__ __forceinline__ void el_phase(const KAS Args& a, int i, const int tid_, const int bid, const int nblk) {
;     ...
;             for (int e = 0; e < 8; ++e) { const float z = zc[e] + (zp[e] - zc[e]) * mu[c0 + e];
;                 o[e] = (c0 < 64) ? (2.0f * fast_sigmoid(2.0f * z) - 1.0f) : (c0 < 128 ? z : fast_sigmoid(z)); }
.LBB0_224:
	s_or_b64 exec, exec, s[2:3]
	v_and_b32_e32 v28, 0xffff0000, v29
	v_and_b32_e32 v29, 0xffff0000, v33
	v_mov_b32_e32 v33, v49
	v_sub_f32_e32 v29, v29, v28
	v_fmac_f32_e32 v28, v29, v33
	s_and_saveexec_b64 s[2:3], s[6:7]
	s_xor_b64 s[2:3], exec, s[2:3]
	s_cbranch_execz .LBB0_226
	v_mul_f32_e32 v29, 0xbfb8aa3b, v28
	v_exp_f32_e32 v29, v29
	s_nop 0
	v_add_f32_e32 v29, 1.0, v29
	v_rcp_f32_e32 v29, v29
	s_nop 0
	v_cndmask_b32_e32 v33, v29, v28, vcc

; __device__ __forceinline__ float fast_sigmoid(float x) { return __builtin_amdgcn_rcpf(1.0f + __builtin_amdgcn_exp2f(-1.4426950408889634f * x)); }
; __device__ __forceinline__ void el_phase(const KAS Args& a, int i, const int tid_, const int bid, const int nblk) {
;     ...
;             for (int e = 0; e < 8; ++e) { const float z = zc[e] + (zp[e] - zc[e]) * mu[c0 + e];
;                 o[e] = (c0 < 64) ? (2.0f * fast_sigmoid(2.0f * z) - 1.0f) : (c0 < 128 ? z : fast_sigmoid(z)); }
.LBB0_228:
	s_or_b64 exec, exec, s[2:3]
	v_mov_b32_e32 v44, v50
	v_lshlrev_b32_e32 v28, 16, v30
	v_lshlrev_b32_e32 v29, 16, v34
	v_sub_f32_e32 v29, v29, v28
	v_fmac_f32_e32 v28, v29, v44
	s_and_saveexec_b64 s[2:3], s[6:7]
	s_xor_b64 s[2:3], exec, s[2:3]
	s_cbranch_execz .LBB0_230
	v_mul_f32_e32 v29, 0xbfb8aa3b, v28
	v_exp_f32_e32 v29, v29
	s_nop 0
	v_add_f32_e32 v29, 1.0, v29
	v_rcp_f32_e32 v29, v29
	s_nop 0
	v_cndmask_b32_e32 v44, v29, v28, vcc

; __device__ __forceinline__ float fast_sigmoid(float x) { return __builtin_amdgcn_rcpf(1.0f + __builtin_amdgcn_exp2f(-1.4426950408889634f * x)); }
; __device__ __forceinline__ void el_phase(const KAS Args& a, int i, const int tid_, const int bid, const int nblk) {
;     ...
;             for (int e = 0; e < 8; ++e) { const float z = zc[e] + (zp[e] - zc[e]) * mu[c0 + e];
;                 o[e] = (c0 < 64) ? (2.0f * fast_sigmoid(2.0f * z) - 1.0f) : (c0 < 128 ? z : fast_sigmoid(z)); }
.LBB0_232:
	s_or_b64 exec, exec, s[2:3]
	v_and_b32_e32 v28, 0xffff0000, v30
	v_mov_b32_e32 v30, v51
	v_and_b32_e32 v29, 0xffff0000, v34
	v_sub_f32_e32 v29, v29, v28
	v_fmac_f32_e32 v28, v29, v30
	s_and_saveexec_b64 s[2:3], s[6:7]
	s_xor_b64 s[2:3], exec, s[2:3]
	s_cbranch_execz .LBB0_234
	v_mul_f32_e32 v29, 0xbfb8aa3b, v28
	v_exp_f32_e32 v29, v29
	s_nop 0
	v_add_f32_e32 v29, 1.0, v29
	v_rcp_f32_e32 v29, v29
	s_nop 0
	v_cndmask_b32_e32 v30, v29, v28, vcc

; __device__ __forceinline__ float fast_sigmoid(float x) { return __builtin_amdgcn_rcpf(1.0f + __builtin_amdgcn_exp2f(-1.4426950408889634f * x)); }
; __device__ __forceinline__ void el_phase(const KAS Args& a, int i, const int tid_, const int bid, const int nblk) {
;     ...
;             for (int e = 0; e < 8; ++e) { const float z = zc[e] + (zp[e] - zc[e]) * mu[c0 + e];
;                 o[e] = (c0 < 64) ? (2.0f * fast_sigmoid(2.0f * z) - 1.0f) : (c0 < 128 ? z : fast_sigmoid(z)); }
.LBB0_236:
	s_or_b64 exec, exec, s[2:3]
	v_mov_b32_e32 v34, v52
	v_lshlrev_b32_e32 v28, 16, v31
	v_lshlrev_b32_e32 v29, 16, v35
	v_sub_f32_e32 v29, v29, v28
	v_fmac_f32_e32 v28, v29, v34
	s_and_saveexec_b64 s[2:3], s[6:7]
	s_xor_b64 s[2:3], exec, s[2:3]
	s_cbranch_execz .LBB0_238
	v_mul_f32_e32 v29, 0xbfb8aa3b, v28
	v_exp_f32_e32 v29, v29
	s_nop 0
	v_add_f32_e32 v29, 1.0, v29
	v_rcp_f32_e32 v29, v29
	s_nop 0
	v_cndmask_b32_e32 v34, v29, v28, vcc

; __device__ __forceinline__ float fast_sigmoid(float x) { return __builtin_amdgcn_rcpf(1.0f + __builtin_amdgcn_exp2f(-1.4426950408889634f * x)); }
; __device__ __forceinline__ void el_phase(const KAS Args& a, int i, const int tid_, const int bid, const int nblk) {
;     ...
;             for (int e = 0; e < 8; ++e) { const float z = zc[e] + (zp[e] - zc[e]) * mu[c0 + e];
;                 o[e] = (c0 < 64) ? (2.0f * fast_sigmoid(2.0f * z) - 1.0f) : (c0 < 128 ? z : fast_sigmoid(z)); }
.LBB0_240:
	s_or_b64 exec, exec, s[2:3]
	v_and_b32_e32 v28, 0xffff0000, v31
	v_mov_b32_e32 v31, v53
	v_and_b32_e32 v29, 0xffff0000, v35
	v_sub_f32_e32 v29, v29, v28
	v_fmac_f32_e32 v28, v29, v31
	s_and_saveexec_b64 s[2:3], s[6:7]
	s_xor_b64 s[2:3], exec, s[2:3]
	s_cbranch_execz .LBB0_242
	v_mul_f32_e32 v29, 0xbfb8aa3b, v28
	v_exp_f32_e32 v29, v29
	s_nop 0
	v_add_f32_e32 v29, 1.0, v29
	v_rcp_f32_e32 v29, v29
	s_nop 0
	v_cndmask_b32_e32 v31, v29, v28, vcc

; __device__ __forceinline__ float fast_sigmoid(float x) { return __builtin_amdgcn_rcpf(1.0f + __builtin_amdgcn_exp2f(-1.4426950408889634f * x)); }
; __device__ __forceinline__ u32x4 pack8(const float (&f)[8]) { return (u32x4){pk2(f[0], f[1]), pk2(f[2], f[3]), pk2(f[4], f[5]), pk2(f[6], f[7])}; }
; __device__ __forceinline__ void el_phase(const KAS Args& a, int i, const int tid_, const int bid, const int nblk) {
;     ...
;             for (int e = 0; e < 8; ++e) { const float z = zc[e] + (zp[e] - zc[e]) * mu[c0 + e];
;                 o[e] = (c0 < 64) ? (2.0f * fast_sigmoid(2.0f * z) - 1.0f) : (c0 < 128 ? z : fast_sigmoid(z)); }
;             *(u32x4*)(LA + (size_t)m * LAC + c0) = pack8(o); } }
.LBB0_244:
	s_or_b64 exec, exec, s[2:3]
	v_lshl_add_u64 v[28:29], s[16:17], 0, v[2:3]
	v_cvt_pk_bf16_f32 v44, v44, v30
	v_cvt_pk_bf16_f32 v45, v34, v31
	v_lshlrev_b64 v[30:31], 9, v[36:37]
	v_cvt_pk_bf16_f32 v42, v42, v32
	v_cvt_pk_bf16_f32 v43, v43, v33
	v_lshl_add_u64 v[30:31], v[28:29], 0, v[30:31]
	global_store_dwordx4 v[30:31], v[42:45], off
	s_and_saveexec_b64 s[22:23], s[12:13]
	s_cbranch_execz .LBB0_203
	v_mov_b32_e32 v31, v46
	v_lshlrev_b32_e32 v30, 16, v24
	v_lshlrev_b32_e32 v2, 16, v20
	v_sub_f32_e32 v2, v2, v30
	v_fmac_f32_e32 v30, v2, v31
	s_and_saveexec_b64 s[2:3], s[6:7]
	s_xor_b64 s[2:3], exec, s[2:3]
	s_cbranch_execz .LBB0_247
	v_mul_f32_e32 v2, 0xbfb8aa3b, v30
	v_exp_f32_e32 v2, v2
	s_nop 0
	v_add_f32_e32 v2, 1.0, v2
	v_rcp_f32_e32 v2, v2
	s_nop 0
	v_cndmask_b32_e32 v2, v2, v30, vcc

; __device__ __forceinline__ float fast_sigmoid(float x) { return __builtin_amdgcn_rcpf(1.0f + __builtin_amdgcn_exp2f(-1.4426950408889634f * x)); }
; __device__ __forceinline__ void el_phase(const KAS Args& a, int i, const int tid_, const int bid, const int nblk) {
;     ...
;             for (int e = 0; e < 8; ++e) { const float z = zc[e] + (zp[e] - zc[e]) * mu[c0 + e];
;                 o[e] = (c0 < 64) ? (2.0f * fast_sigmoid(2.0f * z) - 1.0f) : (c0 < 128 ? z : fast_sigmoid(z)); }
.LBB0_249:
	s_or_b64 exec, exec, s[2:3]
	v_mov_b32_e32 v30, v47
	v_and_b32_e32 v24, 0xffff0000, v24
	v_and_b32_e32 v20, 0xffff0000, v20
	v_sub_f32_e32 v20, v20, v24
	v_fmac_f32_e32 v24, v20, v30
	s_and_saveexec_b64 s[2:3], s[6:7]
	s_xor_b64 s[2:3], exec, s[2:3]
	s_cbranch_execz .LBB0_251
	v_mul_f32_e32 v20, 0xbfb8aa3b, v24
	v_exp_f32_e32 v20, v20
	s_nop 0
	v_add_f32_e32 v20, 1.0, v20
	v_rcp_f32_e32 v20, v20
	s_nop 0
	v_cndmask_b32_e32 v20, v20, v24, vcc

; __device__ __forceinline__ float fast_sigmoid(float x) { return __builtin_amdgcn_rcpf(1.0f + __builtin_amdgcn_exp2f(-1.4426950408889634f * x)); }
; __device__ __forceinline__ void el_phase(const KAS Args& a, int i, const int tid_, const int bid, const int nblk) {
;     ...
;             for (int e = 0; e < 8; ++e) { const float z = zc[e] + (zp[e] - zc[e]) * mu[c0 + e];
;                 o[e] = (c0 < 64) ? (2.0f * fast_sigmoid(2.0f * z) - 1.0f) : (c0 < 128 ? z : fast_sigmoid(z)); }
.LBB0_253:
	s_or_b64 exec, exec, s[2:3]
	v_mov_b32_e32 v31, v48
	v_lshlrev_b32_e32 v30, 16, v25
	v_lshlrev_b32_e32 v24, 16, v21
	v_sub_f32_e32 v24, v24, v30
	v_fmac_f32_e32 v30, v24, v31
	s_and_saveexec_b64 s[2:3], s[6:7]
	s_xor_b64 s[2:3], exec, s[2:3]
	s_cbranch_execz .LBB0_255
	v_mul_f32_e32 v24, 0xbfb8aa3b, v30
	v_exp_f32_e32 v24, v24
	s_nop 0
	v_add_f32_e32 v24, 1.0, v24
	v_rcp_f32_e32 v24, v24
	s_nop 0
	v_cndmask_b32_e32 v24, v24, v30, vcc

; __device__ __forceinline__ float fast_sigmoid(float x) { return __builtin_amdgcn_rcpf(1.0f + __builtin_amdgcn_exp2f(-1.4426950408889634f * x)); }
; __device__ __forceinline__ void el_phase(const KAS Args& a, int i, const int tid_, const int bid, const int nblk) {
;     ...
;             for (int e = 0; e < 8; ++e) { const float z = zc[e] + (zp[e] - zc[e]) * mu[c0 + e];
;                 o[e] = (c0 < 64) ? (2.0f * fast_sigmoid(2.0f * z) - 1.0f) : (c0 < 128 ? z : fast_sigmoid(z)); }
.LBB0_257:
	s_or_b64 exec, exec, s[2:3]
	v_mov_b32_e32 v30, v49
	v_and_b32_e32 v25, 0xffff0000, v25
	v_and_b32_e32 v21, 0xffff0000, v21
	v_sub_f32_e32 v21, v21, v25
	v_fmac_f32_e32 v25, v21, v30
	s_and_saveexec_b64 s[2:3], s[6:7]
	s_xor_b64 s[2:3], exec, s[2:3]
	s_cbranch_execz .LBB0_259
	v_mul_f32_e32 v21, 0xbfb8aa3b, v25
	v_exp_f32_e32 v21, v21
	s_nop 0
	v_add_f32_e32 v21, 1.0, v21
	v_rcp_f32_e32 v21, v21
	s_nop 0
	v_cndmask_b32_e32 v21, v21, v25, vcc

; __device__ __forceinline__ float fast_sigmoid(float x) { return __builtin_amdgcn_rcpf(1.0f + __builtin_amdgcn_exp2f(-1.4426950408889634f * x)); }
; __device__ __forceinline__ void el_phase(const KAS Args& a, int i, const int tid_, const int bid, const int nblk) {
;     ...
;             for (int e = 0; e < 8; ++e) { const float z = zc[e] + (zp[e] - zc[e]) * mu[c0 + e];
;                 o[e] = (c0 < 64) ? (2.0f * fast_sigmoid(2.0f * z) - 1.0f) : (c0 < 128 ? z : fast_sigmoid(z)); }
.LBB0_261:
	s_or_b64 exec, exec, s[2:3]
	v_mov_b32_e32 v31, v50
	v_lshlrev_b32_e32 v30, 16, v26
	v_lshlrev_b32_e32 v25, 16, v22
	v_sub_f32_e32 v25, v25, v30
	v_fmac_f32_e32 v30, v25, v31
	s_and_saveexec_b64 s[2:3], s[6:7]
	s_xor_b64 s[2:3], exec, s[2:3]
	s_cbranch_execz .LBB0_263
	v_mul_f32_e32 v25, 0xbfb8aa3b, v30
	v_exp_f32_e32 v25, v25
	s_nop 0
	v_add_f32_e32 v25, 1.0, v25
	v_rcp_f32_e32 v25, v25
	s_nop 0
	v_cndmask_b32_e32 v25, v25, v30, vcc

; __device__ __forceinline__ float fast_sigmoid(float x) { return __builtin_amdgcn_rcpf(1.0f + __builtin_amdgcn_exp2f(-1.4426950408889634f * x)); }
; __device__ __forceinline__ void el_phase(const KAS Args& a, int i, const int tid_, const int bid, const int nblk) {
;     ...
;             for (int e = 0; e < 8; ++e) { const float z = zc[e] + (zp[e] - zc[e]) * mu[c0 + e];
;                 o[e] = (c0 < 64) ? (2.0f * fast_sigmoid(2.0f * z) - 1.0f) : (c0 < 128 ? z : fast_sigmoid(z)); }
.LBB0_265:
	s_or_b64 exec, exec, s[2:3]
	v_mov_b32_e32 v30, v51
	v_and_b32_e32 v26, 0xffff0000, v26
	v_and_b32_e32 v22, 0xffff0000, v22
	v_sub_f32_e32 v22, v22, v26
	v_fmac_f32_e32 v26, v22, v30
	s_and_saveexec_b64 s[2:3], s[6:7]
	s_xor_b64 s[2:3], exec, s[2:3]
	s_cbranch_execz .LBB0_267
	v_mul_f32_e32 v22, 0xbfb8aa3b, v26
	v_exp_f32_e32 v22, v22
	s_nop 0
	v_add_f32_e32 v22, 1.0, v22
	v_rcp_f32_e32 v22, v22
	s_nop 0
	v_cndmask_b32_e32 v22, v22, v26, vcc

; __device__ __forceinline__ float fast_sigmoid(float x) { return __builtin_amdgcn_rcpf(1.0f + __builtin_amdgcn_exp2f(-1.4426950408889634f * x)); }
; __device__ __forceinline__ void el_phase(const KAS Args& a, int i, const int tid_, const int bid, const int nblk) {
;     ...
;             for (int e = 0; e < 8; ++e) { const float z = zc[e] + (zp[e] - zc[e]) * mu[c0 + e];
;                 o[e] = (c0 < 64) ? (2.0f * fast_sigmoid(2.0f * z) - 1.0f) : (c0 < 128 ? z : fast_sigmoid(z)); }
.LBB0_269:
	s_or_b64 exec, exec, s[2:3]
	v_mov_b32_e32 v31, v52
	v_lshlrev_b32_e32 v30, 16, v27
	v_lshlrev_b32_e32 v26, 16, v23
	v_sub_f32_e32 v26, v26, v30
	v_fmac_f32_e32 v30, v26, v31
	s_and_saveexec_b64 s[2:3], s[6:7]
	s_xor_b64 s[2:3], exec, s[2:3]
	s_cbranch_execz .LBB0_271
	v_mul_f32_e32 v26, 0xbfb8aa3b, v30
	v_exp_f32_e32 v26, v26
	s_nop 0
	v_add_f32_e32 v26, 1.0, v26
	v_rcp_f32_e32 v26, v26
	s_nop 0
	v_cndmask_b32_e32 v26, v26, v30, vcc

; __device__ __forceinline__ float fast_sigmoid(float x) { return __builtin_amdgcn_rcpf(1.0f + __builtin_amdgcn_exp2f(-1.4426950408889634f * x)); }
; __device__ __forceinline__ void el_phase(const KAS Args& a, int i, const int tid_, const int bid, const int nblk) {
;     ...
;             for (int e = 0; e < 8; ++e) { const float z = zc[e] + (zp[e] - zc[e]) * mu[c0 + e];
;                 o[e] = (c0 < 64) ? (2.0f * fast_sigmoid(2.0f * z) - 1.0f) : (c0 < 128 ? z : fast_sigmoid(z)); }
.LBB0_273:
	s_or_b64 exec, exec, s[2:3]
	v_mov_b32_e32 v30, v53
	v_and_b32_e32 v27, 0xffff0000, v27
	v_and_b32_e32 v23, 0xffff0000, v23
	v_sub_f32_e32 v23, v23, v27
	v_fmac_f32_e32 v27, v23, v30
	s_and_saveexec_b64 s[2:3], s[6:7]
	s_xor_b64 s[2:3], exec, s[2:3]
	s_cbranch_execz .LBB0_275
	v_mul_f32_e32 v23, 0xbfb8aa3b, v27
	v_exp_f32_e32 v23, v23
	s_nop 0
	v_add_f32_e32 v23, 1.0, v23
	v_rcp_f32_e32 v23, v23
	s_nop 0
	v_cndmask_b32_e32 v23, v23, v27, vcc

; __device__ __forceinline__ float fast_sigmoid(float x) { return __builtin_amdgcn_rcpf(1.0f + __builtin_amdgcn_exp2f(-1.4426950408889634f * x)); }
; __device__ __forceinline__ u32x4 pack8(const float (&f)[8]) { return (u32x4){pk2(f[0], f[1]), pk2(f[2], f[3]), pk2(f[4], f[5]), pk2(f[6], f[7])}; }
; __device__ __forceinline__ void el_phase(const KAS Args& a, int i, const int tid_, const int bid, const int nblk) {
;     ...
;             for (int e = 0; e < 8; ++e) { const float z = zc[e] + (zp[e] - zc[e]) * mu[c0 + e];
;                 o[e] = (c0 < 64) ? (2.0f * fast_sigmoid(2.0f * z) - 1.0f) : (c0 < 128 ? z : fast_sigmoid(z)); }
;             *(u32x4*)(LA + (size_t)m * LAC + c0) = pack8(o); } }
.LBB0_277:
	s_or_b64 exec, exec, s[2:3]
	v_ashrrev_i32_e32 v30, 5, v39
	v_ashrrev_i32_e32 v31, 31, v30
	v_cvt_pk_bf16_f32 v21, v24, v21
	v_cvt_pk_bf16_f32 v22, v25, v22
	v_lshlrev_b64 v[24:25], 9, v[30:31]
	v_cvt_pk_bf16_f32 v20, v2, v20
	v_cvt_pk_bf16_f32 v23, v26, v23
	v_lshl_add_u64 v[24:25], v[28:29], 0, v[24:25]
	global_store_dwordx4 v[24:25], v[20:23], off
	s_and_b64 exec, exec, s[10:11]
	s_cbranch_execz .LBB0_203
	v_mov_b32_e32 v21, v46
	v_lshlrev_b32_e32 v20, 16, v12
	v_lshlrev_b32_e32 v2, 16, v16
	v_sub_f32_e32 v2, v2, v20
	v_fmac_f32_e32 v20, v2, v21
	s_and_saveexec_b64 s[2:3], s[6:7]
	s_xor_b64 s[2:3], exec, s[2:3]
	s_cbranch_execz .LBB0_280
	v_mul_f32_e32 v2, 0xbfb8aa3b, v20
	v_exp_f32_e32 v2, v2
	s_nop 0
	v_add_f32_e32 v2, 1.0, v2
	v_rcp_f32_e32 v2, v2
	s_nop 0
	v_cndmask_b32_e32 v2, v2, v20, vcc

; __device__ __forceinline__ float fast_sigmoid(float x) { return __builtin_amdgcn_rcpf(1.0f + __builtin_amdgcn_exp2f(-1.4426950408889634f * x)); }
; __device__ __forceinline__ void el_phase(const KAS Args& a, int i, const int tid_, const int bid, const int nblk) {
;     ...
;             for (int e = 0; e < 8; ++e) { const float z = zc[e] + (zp[e] - zc[e]) * mu[c0 + e];
;                 o[e] = (c0 < 64) ? (2.0f * fast_sigmoid(2.0f * z) - 1.0f) : (c0 < 128 ? z : fast_sigmoid(z)); }
.LBB0_282:
	s_or_b64 exec, exec, s[2:3]
	v_and_b32_e32 v20, 0xffff0000, v12
	v_and_b32_e32 v12, 0xffff0000, v16
	v_mov_b32_e32 v16, v47
	v_sub_f32_e32 v12, v12, v20
	v_fmac_f32_e32 v20, v12, v16
	s_and_saveexec_b64 s[2:3], s[6:7]
	s_xor_b64 s[2:3], exec, s[2:3]
	s_cbranch_execz .LBB0_284
	v_mul_f32_e32 v12, 0xbfb8aa3b, v20
	v_exp_f32_e32 v12, v12
	s_nop 0
	v_add_f32_e32 v12, 1.0, v12
	v_rcp_f32_e32 v12, v12
	s_nop 0
	v_cndmask_b32_e32 v12, v12, v20, vcc

; __device__ __forceinline__ float fast_sigmoid(float x) { return __builtin_amdgcn_rcpf(1.0f + __builtin_amdgcn_exp2f(-1.4426950408889634f * x)); }
; __device__ __forceinline__ void el_phase(const KAS Args& a, int i, const int tid_, const int bid, const int nblk) {
;     ...
;             for (int e = 0; e < 8; ++e) { const float z = zc[e] + (zp[e] - zc[e]) * mu[c0 + e];
;                 o[e] = (c0 < 64) ? (2.0f * fast_sigmoid(2.0f * z) - 1.0f) : (c0 < 128 ? z : fast_sigmoid(z)); }
.LBB0_286:
	s_or_b64 exec, exec, s[2:3]
	v_mov_b32_e32 v21, v48
	v_lshlrev_b32_e32 v20, 16, v13
	v_lshlrev_b32_e32 v16, 16, v17
	v_sub_f32_e32 v16, v16, v20
	v_fmac_f32_e32 v20, v16, v21
	s_and_saveexec_b64 s[2:3], s[6:7]
	s_xor_b64 s[2:3], exec, s[2:3]
	s_cbranch_execz .LBB0_288
	v_mul_f32_e32 v16, 0xbfb8aa3b, v20
	v_exp_f32_e32 v16, v16
	s_nop 0
	v_add_f32_e32 v16, 1.0, v16
	v_rcp_f32_e32 v16, v16
	s_nop 0
	v_cndmask_b32_e32 v16, v16, v20, vcc

; __device__ __forceinline__ float fast_sigmoid(float x) { return __builtin_amdgcn_rcpf(1.0f + __builtin_amdgcn_exp2f(-1.4426950408889634f * x)); }
; __device__ __forceinline__ void el_phase(const KAS Args& a, int i, const int tid_, const int bid, const int nblk) {
;     ...
;             for (int e = 0; e < 8; ++e) { const float z = zc[e] + (zp[e] - zc[e]) * mu[c0 + e];
;                 o[e] = (c0 < 64) ? (2.0f * fast_sigmoid(2.0f * z) - 1.0f) : (c0 < 128 ? z : fast_sigmoid(z)); }
.LBB0_290:
	s_or_b64 exec, exec, s[2:3]
	v_and_b32_e32 v20, 0xffff0000, v13
	v_and_b32_e32 v13, 0xffff0000, v17
	v_mov_b32_e32 v17, v49
	v_sub_f32_e32 v13, v13, v20
	v_fmac_f32_e32 v20, v13, v17
	s_and_saveexec_b64 s[2:3], s[6:7]
	s_xor_b64 s[2:3], exec, s[2:3]
	s_cbranch_execz .LBB0_292
	v_mul_f32_e32 v13, 0xbfb8aa3b, v20
	v_exp_f32_e32 v13, v13
	s_nop 0
	v_add_f32_e32 v13, 1.0, v13
	v_rcp_f32_e32 v13, v13
	s_nop 0
	v_cndmask_b32_e32 v13, v13, v20, vcc

; __device__ __forceinline__ float fast_sigmoid(float x) { return __builtin_amdgcn_rcpf(1.0f + __builtin_amdgcn_exp2f(-1.4426950408889634f * x)); }
; __device__ __forceinline__ void el_phase(const KAS Args& a, int i, const int tid_, const int bid, const int nblk) {
;     ...
;             for (int e = 0; e < 8; ++e) { const float z = zc[e] + (zp[e] - zc[e]) * mu[c0 + e];
;                 o[e] = (c0 < 64) ? (2.0f * fast_sigmoid(2.0f * z) - 1.0f) : (c0 < 128 ? z : fast_sigmoid(z)); }
.LBB0_294:
	s_or_b64 exec, exec, s[2:3]
	v_mov_b32_e32 v21, v50
	v_lshlrev_b32_e32 v20, 16, v14
	v_lshlrev_b32_e32 v17, 16, v18
	v_sub_f32_e32 v17, v17, v20
	v_fmac_f32_e32 v20, v17, v21
	s_and_saveexec_b64 s[2:3], s[6:7]
	s_xor_b64 s[2:3], exec, s[2:3]
	s_cbranch_execz .LBB0_296
	v_mul_f32_e32 v17, 0xbfb8aa3b, v20
	v_exp_f32_e32 v17, v17
	s_nop 0
	v_add_f32_e32 v17, 1.0, v17
	v_rcp_f32_e32 v17, v17
	s_nop 0
	v_cndmask_b32_e32 v17, v17, v20, vcc

; __device__ __forceinline__ float fast_sigmoid(float x) { return __builtin_amdgcn_rcpf(1.0f + __builtin_amdgcn_exp2f(-1.4426950408889634f * x)); }
; __device__ __forceinline__ void el_phase(const KAS Args& a, int i, const int tid_, const int bid, const int nblk) {
;     ...
;             for (int e = 0; e < 8; ++e) { const float z = zc[e] + (zp[e] - zc[e]) * mu[c0 + e];
;                 o[e] = (c0 < 64) ? (2.0f * fast_sigmoid(2.0f * z) - 1.0f) : (c0 < 128 ? z : fast_sigmoid(z)); }
.LBB0_298:
	s_or_b64 exec, exec, s[2:3]
	v_and_b32_e32 v20, 0xffff0000, v14
	v_and_b32_e32 v14, 0xffff0000, v18
	v_mov_b32_e32 v18, v51
	v_sub_f32_e32 v14, v14, v20
	v_fmac_f32_e32 v20, v14, v18
	s_and_saveexec_b64 s[2:3], s[6:7]
	s_xor_b64 s[2:3], exec, s[2:3]
	s_cbranch_execz .LBB0_300
	v_mul_f32_e32 v14, 0xbfb8aa3b, v20
	v_exp_f32_e32 v14, v14
	s_nop 0
	v_add_f32_e32 v14, 1.0, v14
	v_rcp_f32_e32 v14, v14
	s_nop 0
	v_cndmask_b32_e32 v14, v14, v20, vcc

; __device__ __forceinline__ float fast_sigmoid(float x) { return __builtin_amdgcn_rcpf(1.0f + __builtin_amdgcn_exp2f(-1.4426950408889634f * x)); }
; __device__ __forceinline__ void el_phase(const KAS Args& a, int i, const int tid_, const int bid, const int nblk) {
;     ...
;             for (int e = 0; e < 8; ++e) { const float z = zc[e] + (zp[e] - zc[e]) * mu[c0 + e];
;                 o[e] = (c0 < 64) ? (2.0f * fast_sigmoid(2.0f * z) - 1.0f) : (c0 < 128 ? z : fast_sigmoid(z)); }
.LBB0_302:
	s_or_b64 exec, exec, s[2:3]
	v_mov_b32_e32 v21, v52
	v_lshlrev_b32_e32 v20, 16, v15
	v_lshlrev_b32_e32 v18, 16, v19
	v_sub_f32_e32 v18, v18, v20
	v_fmac_f32_e32 v20, v18, v21
	s_and_saveexec_b64 s[2:3], s[6:7]
	s_xor_b64 s[2:3], exec, s[2:3]
	s_cbranch_execz .LBB0_304
	v_mul_f32_e32 v18, 0xbfb8aa3b, v20
	v_exp_f32_e32 v18, v18
	s_nop 0
	v_add_f32_e32 v18, 1.0, v18
	v_rcp_f32_e32 v18, v18
	s_nop 0
	v_cndmask_b32_e32 v18, v18, v20, vcc

; __device__ __forceinline__ float fast_sigmoid(float x) { return __builtin_amdgcn_rcpf(1.0f + __builtin_amdgcn_exp2f(-1.4426950408889634f * x)); }
; __device__ __forceinline__ void el_phase(const KAS Args& a, int i, const int tid_, const int bid, const int nblk) {
;     ...
;             for (int e = 0; e < 8; ++e) { const float z = zc[e] + (zp[e] - zc[e]) * mu[c0 + e];
;                 o[e] = (c0 < 64) ? (2.0f * fast_sigmoid(2.0f * z) - 1.0f) : (c0 < 128 ? z : fast_sigmoid(z)); }
.LBB0_306:
	s_or_b64 exec, exec, s[2:3]
	v_mov_b32_e32 v20, v53
	v_and_b32_e32 v15, 0xffff0000, v15
	v_and_b32_e32 v19, 0xffff0000, v19
	v_sub_f32_e32 v19, v19, v15
	v_fmac_f32_e32 v15, v19, v20
	s_and_saveexec_b64 s[2:3], s[6:7]
	s_xor_b64 s[2:3], exec, s[2:3]
	s_cbranch_execz .LBB0_308
	v_mul_f32_e32 v19, 0xbfb8aa3b, v15
	v_exp_f32_e32 v19, v19
	s_nop 0
	v_add_f32_e32 v19, 1.0, v19
	v_rcp_f32_e32 v19, v19
	s_nop 0
	v_cndmask_b32_e32 v19, v19, v15, vcc

; __device__ __forceinline__ float fast_sigmoid(float x) { return __builtin_amdgcn_rcpf(1.0f + __builtin_amdgcn_exp2f(-1.4426950408889634f * x)); }
; __device__ __forceinline__ u32x4 pack8(const float (&f)[8]) { return (u32x4){pk2(f[0], f[1]), pk2(f[2], f[3]), pk2(f[4], f[5]), pk2(f[6], f[7])}; }
; __device__ __forceinline__ void el_phase(const KAS Args& a, int i, const int tid_, const int bid, const int nblk) {
;     ...
;             for (int e = 0; e < 8; ++e) { const float z = zc[e] + (zp[e] - zc[e]) * mu[c0 + e];
;                 o[e] = (c0 < 64) ? (2.0f * fast_sigmoid(2.0f * z) - 1.0f) : (c0 < 128 ? z : fast_sigmoid(z)); }
;             *(u32x4*)(LA + (size_t)m * LAC + c0) = pack8(o); } }
.LBB0_310:
	s_or_b64 exec, exec, s[2:3]
	v_ashrrev_i32_e32 v20, 5, v41
	v_ashrrev_i32_e32 v21, 31, v20
	v_cvt_pk_bf16_f32 v13, v16, v13
	v_cvt_pk_bf16_f32 v14, v17, v14
	v_lshlrev_b64 v[16:17], 9, v[20:21]
	v_cvt_pk_bf16_f32 v12, v2, v12
	v_cvt_pk_bf16_f32 v15, v18, v19
	v_lshl_add_u64 v[16:17], v[28:29], 0, v[16:17]
	global_store_dwordx4 v[16:17], v[12:15], off
	s_and_b64 exec, exec, s[8:9]
	s_cbranch_execz .LBB0_203
	v_mov_b32_e32 v13, v46
	v_lshlrev_b32_e32 v12, 16, v8
	v_lshlrev_b32_e32 v2, 16, v4
	v_sub_f32_e32 v2, v2, v12
	v_fmac_f32_e32 v12, v2, v13
	s_and_saveexec_b64 s[2:3], s[6:7]
	s_xor_b64 s[2:3], exec, s[2:3]
	s_cbranch_execz .LBB0_313
	v_mul_f32_e32 v2, 0xbfb8aa3b, v12
	v_exp_f32_e32 v2, v2
	s_nop 0
	v_add_f32_e32 v2, 1.0, v2
	v_rcp_f32_e32 v2, v2
	s_nop 0
	v_cndmask_b32_e32 v2, v2, v12, vcc

; __device__ __forceinline__ float fast_sigmoid(float x) { return __builtin_amdgcn_rcpf(1.0f + __builtin_amdgcn_exp2f(-1.4426950408889634f * x)); }
; __device__ __forceinline__ void el_phase(const KAS Args& a, int i, const int tid_, const int bid, const int nblk) {
;     ...
;             for (int e = 0; e < 8; ++e) { const float z = zc[e] + (zp[e] - zc[e]) * mu[c0 + e];
;                 o[e] = (c0 < 64) ? (2.0f * fast_sigmoid(2.0f * z) - 1.0f) : (c0 < 128 ? z : fast_sigmoid(z)); }
.LBB0_315:
	s_or_b64 exec, exec, s[2:3]
	v_mov_b32_e32 v12, v47
	v_and_b32_e32 v8, 0xffff0000, v8
	v_and_b32_e32 v4, 0xffff0000, v4
	v_sub_f32_e32 v4, v4, v8
	v_fmac_f32_e32 v8, v4, v12
	s_and_saveexec_b64 s[2:3], s[6:7]
	s_xor_b64 s[2:3], exec, s[2:3]
	s_cbranch_execz .LBB0_317
	v_mul_f32_e32 v4, 0xbfb8aa3b, v8
	v_exp_f32_e32 v4, v4
	s_nop 0
	v_add_f32_e32 v4, 1.0, v4
	v_rcp_f32_e32 v4, v4
	s_nop 0
	v_cndmask_b32_e32 v4, v4, v8, vcc

; __device__ __forceinline__ float fast_sigmoid(float x) { return __builtin_amdgcn_rcpf(1.0f + __builtin_amdgcn_exp2f(-1.4426950408889634f * x)); }
; __device__ __forceinline__ void el_phase(const KAS Args& a, int i, const int tid_, const int bid, const int nblk) {
;     ...
;             for (int e = 0; e < 8; ++e) { const float z = zc[e] + (zp[e] - zc[e]) * mu[c0 + e];
;                 o[e] = (c0 < 64) ? (2.0f * fast_sigmoid(2.0f * z) - 1.0f) : (c0 < 128 ? z : fast_sigmoid(z)); }
.LBB0_319:
	s_or_b64 exec, exec, s[2:3]
	v_mov_b32_e32 v13, v48
	v_lshlrev_b32_e32 v12, 16, v9
	v_lshlrev_b32_e32 v8, 16, v5
	v_sub_f32_e32 v8, v8, v12
	v_fmac_f32_e32 v12, v8, v13
	s_and_saveexec_b64 s[2:3], s[6:7]
	s_xor_b64 s[2:3], exec, s[2:3]
	s_cbranch_execz .LBB0_321
	v_mul_f32_e32 v8, 0xbfb8aa3b, v12
	v_exp_f32_e32 v8, v8
	s_nop 0
	v_add_f32_e32 v8, 1.0, v8
	v_rcp_f32_e32 v8, v8
	s_nop 0
	v_cndmask_b32_e32 v8, v8, v12, vcc

; __device__ __forceinline__ float fast_sigmoid(float x) { return __builtin_amdgcn_rcpf(1.0f + __builtin_amdgcn_exp2f(-1.4426950408889634f * x)); }
; __device__ __forceinline__ void el_phase(const KAS Args& a, int i, const int tid_, const int bid, const int nblk) {
;     ...
;             for (int e = 0; e < 8; ++e) { const float z = zc[e] + (zp[e] - zc[e]) * mu[c0 + e];
;                 o[e] = (c0 < 64) ? (2.0f * fast_sigmoid(2.0f * z) - 1.0f) : (c0 < 128 ? z : fast_sigmoid(z)); }
.LBB0_323:
	s_or_b64 exec, exec, s[2:3]
	v_mov_b32_e32 v12, v49
	v_and_b32_e32 v9, 0xffff0000, v9
	v_and_b32_e32 v5, 0xffff0000, v5
	v_sub_f32_e32 v5, v5, v9
	v_fmac_f32_e32 v9, v5, v12
	s_and_saveexec_b64 s[2:3], s[6:7]
	s_xor_b64 s[2:3], exec, s[2:3]
	s_cbranch_execz .LBB0_325
	v_mul_f32_e32 v5, 0xbfb8aa3b, v9
	v_exp_f32_e32 v5, v5
	s_nop 0
	v_add_f32_e32 v5, 1.0, v5
	v_rcp_f32_e32 v5, v5
	s_nop 0
	v_cndmask_b32_e32 v5, v5, v9, vcc

; __device__ __forceinline__ float fast_sigmoid(float x) { return __builtin_amdgcn_rcpf(1.0f + __builtin_amdgcn_exp2f(-1.4426950408889634f * x)); }
; __device__ __forceinline__ void el_phase(const KAS Args& a, int i, const int tid_, const int bid, const int nblk) {
;     ...
;             for (int e = 0; e < 8; ++e) { const float z = zc[e] + (zp[e] - zc[e]) * mu[c0 + e];
;                 o[e] = (c0 < 64) ? (2.0f * fast_sigmoid(2.0f * z) - 1.0f) : (c0 < 128 ? z : fast_sigmoid(z)); }
.LBB0_327:
	s_or_b64 exec, exec, s[2:3]
	v_mov_b32_e32 v13, v50
	v_lshlrev_b32_e32 v12, 16, v10
	v_lshlrev_b32_e32 v9, 16, v6
	v_sub_f32_e32 v9, v9, v12
	v_fmac_f32_e32 v12, v9, v13
	s_and_saveexec_b64 s[2:3], s[6:7]
	s_xor_b64 s[2:3], exec, s[2:3]
	s_cbranch_execz .LBB0_329
	v_mul_f32_e32 v9, 0xbfb8aa3b, v12
	v_exp_f32_e32 v9, v9
	s_nop 0
	v_add_f32_e32 v9, 1.0, v9
	v_rcp_f32_e32 v9, v9
	s_nop 0
	v_cndmask_b32_e32 v9, v9, v12, vcc

; __device__ __forceinline__ float fast_sigmoid(float x) { return __builtin_amdgcn_rcpf(1.0f + __builtin_amdgcn_exp2f(-1.4426950408889634f * x)); }
; __device__ __forceinline__ void el_phase(const KAS Args& a, int i, const int tid_, const int bid, const int nblk) {
;     ...
;             for (int e = 0; e < 8; ++e) { const float z = zc[e] + (zp[e] - zc[e]) * mu[c0 + e];
;                 o[e] = (c0 < 64) ? (2.0f * fast_sigmoid(2.0f * z) - 1.0f) : (c0 < 128 ? z : fast_sigmoid(z)); }
.LBB0_331:
	s_or_b64 exec, exec, s[2:3]
	v_mov_b32_e32 v12, v51
	v_and_b32_e32 v10, 0xffff0000, v10
	v_and_b32_e32 v6, 0xffff0000, v6
	v_sub_f32_e32 v6, v6, v10
	v_fmac_f32_e32 v10, v6, v12
	s_and_saveexec_b64 s[2:3], s[6:7]
	s_xor_b64 s[2:3], exec, s[2:3]
	s_cbranch_execz .LBB0_333
	v_mul_f32_e32 v6, 0xbfb8aa3b, v10
	v_exp_f32_e32 v6, v6
	s_nop 0
	v_add_f32_e32 v6, 1.0, v6
	v_rcp_f32_e32 v6, v6
	s_nop 0
	v_cndmask_b32_e32 v6, v6, v10, vcc

; __device__ __forceinline__ float fast_sigmoid(float x) { return __builtin_amdgcn_rcpf(1.0f + __builtin_amdgcn_exp2f(-1.4426950408889634f * x)); }
; __device__ __forceinline__ void el_phase(const KAS Args& a, int i, const int tid_, const int bid, const int nblk) {
;     ...
;             for (int e = 0; e < 8; ++e) { const float z = zc[e] + (zp[e] - zc[e]) * mu[c0 + e];
;                 o[e] = (c0 < 64) ? (2.0f * fast_sigmoid(2.0f * z) - 1.0f) : (c0 < 128 ? z : fast_sigmoid(z)); }
.LBB0_335:
	s_or_b64 exec, exec, s[2:3]
	v_mov_b32_e32 v13, v52
	v_lshlrev_b32_e32 v12, 16, v11
	v_lshlrev_b32_e32 v10, 16, v7
	v_sub_f32_e32 v10, v10, v12
	v_fmac_f32_e32 v12, v10, v13
	s_and_saveexec_b64 s[2:3], s[6:7]
	s_xor_b64 s[2:3], exec, s[2:3]
	s_cbranch_execz .LBB0_337
	v_mul_f32_e32 v10, 0xbfb8aa3b, v12
	v_exp_f32_e32 v10, v10
	s_nop 0
	v_add_f32_e32 v10, 1.0, v10
	v_rcp_f32_e32 v10, v10
	s_nop 0
	v_cndmask_b32_e32 v10, v10, v12, vcc

; __device__ __forceinline__ float fast_sigmoid(float x) { return __builtin_amdgcn_rcpf(1.0f + __builtin_amdgcn_exp2f(-1.4426950408889634f * x)); }
; __device__ __forceinline__ void el_phase(const KAS Args& a, int i, const int tid_, const int bid, const int nblk) {
;     ...
;             for (int e = 0; e < 8; ++e) { const float z = zc[e] + (zp[e] - zc[e]) * mu[c0 + e];
;                 o[e] = (c0 < 64) ? (2.0f * fast_sigmoid(2.0f * z) - 1.0f) : (c0 < 128 ? z : fast_sigmoid(z)); }
.LBB0_339:
	s_or_b64 exec, exec, s[2:3]
	v_mov_b32_e32 v1, v53
	v_and_b32_e32 v0, 0xffff0000, v11
	v_and_b32_e32 v7, 0xffff0000, v7
	v_sub_f32_e32 v7, v7, v0
	v_fmac_f32_e32 v0, v7, v1
	s_and_saveexec_b64 s[2:3], s[6:7]
	s_xor_b64 s[2:3], exec, s[2:3]
	s_cbranch_execz .LBB0_341
	v_mul_f32_e32 v1, 0xbfb8aa3b, v0
	v_exp_f32_e32 v1, v1
	s_nop 0
	v_add_f32_e32 v1, 1.0, v1
	v_rcp_f32_e32 v1, v1
	s_nop 0
	v_cndmask_b32_e32 v1, v1, v0, vcc
